# FoX prologue: key-bias (CK) load consumed after the conv-load wait (its own vmcnt(0) removed), so the prologue's two memory round trips overlap
# speedup vs baseline: 1.0042x; 1.0028x over previous
; #define LAS __attribute__((address_space(3)))
; __device__ __forceinline__ unsigned cvtpk(float lo, float hi) { f32x2 v = {lo, hi}; bf16x2_t b = __builtin_convertvector(v, bf16x2_t); return __builtin_bit_cast(unsigned, b); }
; __device__ __forceinline__ float bf_hi_part(float x) { return __uint_as_float(cvtpk(x, 0.f) << 16); }
; __device__ __forceinline__ void prompt_unit_fox(const Args& a, int l, int b, int h, int qb, LAS unsigned char* lds) {
;     ...
;     ATT_DMA2(NP - 1, 0);
;     { const int idx = tid * 4; if (idx < q0 + 256) { const f32x4 c = *(const f32x4*)((const float*)(a.ws + WS_CKP) + (size_t)(b * 8 + h) * T + idx); *(LAS f32x4*)(lds + F_CK + idx * 4) = c;
; #pragma unroll
;         for (int e = 0; e < 4; ++e) { const float h1 = bf_hi_part(c[e]), r1 = c[e] - h1, h2 = bf_hi_part(r1), r2 = r1 - h2; ((LAS u32x2*)(lds + F_AUG))[idx + e] = (u32x2){cvtpk(h1, h2), cvtpk(r2, -1.0f)}; } } }
;     bf16x8 qr[4];
;     { const bf16* Qw = (const bf16*)(a.ws + WS_Q) + (rowb + q0 + wid * 32 + r32) * D + col;
; #pragma unroll
;       for (int d0 = 0; d0 < 4; ++d0) qr[d0] = *(const bf16x8*)(Qw + d0 * 16 + hi * 8); }
;     const lds_cptr vp0 = (lds_cptr)lds + F_V + ((lane >> 4) & 1) * 32 + (lane & 3) * 8 + (4 * hi + ((lane & 15) >> 2)) * 64;
;     const int ql = 32 * (wid & 1) + r32, qlim = ql + 1;
;     LAS float* wsf = (LAS float*)(lds + F_WSF) + wid * 64;
;     FoxState st; st.m = 0.f; st.l = 0.f; st.mq = (bf16x8){}; st.o[0] = (f32x16){}; st.o[1] = (f32x16){};
;     PairP pp; bool pending = false;
; #pragma unroll
;     for (int i = 0; i < 8; ++i) pp.w[i] = (u32x4){0u, 0u, 0u, 0u};
;     { ConvRegs cv; conv_load(cv, a, rowb + q0 + wid * 32, col, lane); conv_store<0>(cv, a, l, h, rowb + q0 + wid * 32, lane); }
.LBB0_309:
	s_andn2_b32 s6, 7, s76
	v_mov_b32_e32 v19, v0
	s_lshl_b32 s7, s6, 8
	s_lshr_b32 s5, s76, 6
	s_bfe_u32 s9, s76, 0x30003
	s_add_i32 s10, s7, 0x100
	v_readfirstlane_b32 s3, v19
	s_ashr_i32 s77, s3, 6
	s_lshr_b32 s11, s10, 7
	s_lshl_b32 s4, s9, 6
	s_lshl_b32 s8, s5, 22
	s_add_u32 s0, s94, s8
	s_addc_u32 s1, s95, 0
	v_writelane_b32 v237, s9, 9
	s_lshl_b32 s9, s9, 7
	s_add_u32 s0, s0, s9
	s_addc_u32 s1, s1, 0
	v_readlane_b32 s12, v242, 20
	v_readlane_b32 s13, v242, 21
	s_add_u32 s8, s12, s8
	v_and_b32_e32 v20, 63, v19
	s_addc_u32 s12, s13, 0
	s_add_u32 s8, s8, s9
	v_lshlrev_b32_e32 v4, 11, v20
	s_addc_u32 s9, s12, 0
	v_lshl_add_u64 v[2:3], s[0:1], 0, v[4:5]
	s_lshl_b32 s0, s77, 3
	s_ashr_i32 s1, s0, 31
	v_lshl_add_u64 v[176:177], s[0:1], 1, v[2:3]
	s_lshl_b32 s0, s77, 4
	v_bfe_u32 v1, v19, 2, 4
	v_and_or_b32 v1, s0, 48, v1
	s_ashr_i32 s0, s3, 3
	v_lshlrev_b32_e32 v4, 11, v1
	s_andn2_b32 s0, s0, 31
	v_lshlrev_b32_e32 v1, 3, v19
	v_lshl_add_u64 v[2:3], s[8:9], 0, v[4:5]
	s_ashr_i32 s1, s0, 31
	v_and_b32_e32 v6, 24, v1
	s_add_i32 s90, s11, -1
	s_mov_b32 s91, s87
	v_lshl_add_u64 v[2:3], s[0:1], 1, v[2:3]
	v_lshlrev_b32_e32 v4, 1, v6
	s_lshl_b64 s[0:1], s[90:91], 18
	s_lshl_b32 s79, s77, 10
	v_lshl_add_u64 v[178:179], v[2:3], 0, v[4:5]
	v_lshl_add_u64 v[2:3], v[176:177], 0, s[0:1]
	s_add_i32 s79, s79, 0
	s_mov_b32 s8, m0
	s_mov_b32 m0, s79
	s_nop 0
	global_load_lds_dwordx4 v[2:3], off
	s_mov_b32 m0, s8
	s_mov_b64 s[12:13], 0x20000
	v_lshl_add_u64 v[2:3], v[2:3], 0, s[12:13]
	s_add_i32 s84, s79, 0x2000
	s_mov_b32 s8, m0
	s_mov_b32 m0, s84
	s_nop 0
	global_load_lds_dwordx4 v[2:3], off
	s_mov_b32 m0, s8
	v_lshl_add_u64 v[2:3], v[178:179], 0, s[0:1]
	s_add_i32 s85, s79, 0xc000
	s_mov_b32 s0, m0
	s_mov_b32 m0, s85
	s_nop 0
	global_load_lds_dwordx4 v[2:3], off
	s_mov_b32 m0, s0
	v_lshl_add_u64 v[2:3], v[2:3], 0, s[12:13]
	s_add_i32 s76, s79, 0xe000
	s_mov_b32 s0, m0
	s_mov_b32 m0, s76
	s_nop 0
	global_load_lds_dwordx4 v[2:3], off
	s_mov_b32 m0, s0
	v_lshlrev_b32_e32 v2, 2, v19
	v_cmp_gt_i32_e32 vcc, s10, v2
	s_mov_b32 s83, vcc_lo
	s_and_saveexec_b64 s[0:1], vcc
	s_cbranch_execz .LBB0_311
	v_readlane_b32 s9, v237, 9
	s_lshl_b32 s8, s5, 14
	s_lshl_b32 s9, s9, 11
	s_or_b32 s8, s9, s8
	s_mov_b32 s9, s87
	s_lshl_b64 s[8:9], s[8:9], 2
	v_readlane_b32 s10, v242, 40
	s_add_u32 s8, s10, s8
	v_readlane_b32 s10, v242, 41
	s_addc_u32 s9, s10, s9
	v_ashrrev_i32_e32 v3, 31, v2
	v_lshl_add_u64 v[8:9], v[2:3], 2, s[8:9]
	global_load_dwordx4 v[92:95], v[8:9], off
	v_lshl_add_u32 v85, v19, 4, 0
	v_add_u32_e32 v85, 0x18000, v85
	v_lshl_add_u32 v86, v2, 3, 0
	v_add_u32_e32 v86, 0x1a800, v86
.LBB0_311:
	s_or_b64 exec, exec, s[0:1]
	s_lshl_b32 s0, s6, 2
	s_ashr_i32 s1, s3, 7
	s_add_i32 s1, s1, s0
	s_ashr_i32 s89, s1, 1
	s_cmp_lt_i32 s77, 4
	s_cselect_b64 s[92:93], -1, 0
	s_lshl_b32 s0, s5, 11
	s_lshl_b32 s5, s77, 5
	s_or_b32 s0, s7, s0
	s_ashr_i32 s1, s5, 31
	s_add_u32 s91, s5, s0
	v_and_b32_e32 v175, 31, v19
	s_addc_u32 s0, s1, 0
	v_or_b32_e32 v168, s91, v175
	v_mov_b32_e32 v169, s0
	v_lshrrev_b32_e32 v1, 3, v20
	v_lshlrev_b64 v[2:3], 11, v[168:169]
	v_or_b32_e32 v168, s91, v1
	v_lshlrev_b32_e32 v4, 3, v20
	v_lshlrev_b64 v[170:171], 11, v[168:169]
	s_lshl_b32 s74, s4, 1
	s_mov_b32 s75, s87
	v_and_b32_e32 v174, 56, v4
	v_lshl_add_u64 v[8:9], s[94:95], 0, v[170:171]
	v_lshl_add_u64 v[8:9], v[8:9], 0, s[74:75]
	v_mov_b32_e32 v4, v174
	v_readlane_b32 s6, v242, 20
	v_lshl_add_u64 v[8:9], v[8:9], 0, v[4:5]
	v_readlane_b32 s7, v242, 21
	global_load_dwordx2 v[24:25], v[8:9], off offset:64
	global_load_dwordx2 v[22:23], v[8:9], off
	v_or_b32_e32 v58, 0x4000, v170
	v_lshl_add_u64 v[8:9], s[6:7], 0, v[170:171]
	v_lshl_add_u64 v[8:9], v[8:9], 0, s[74:75]
	v_lshl_add_u64 v[8:9], v[8:9], 0, v[4:5]
	v_mov_b32_e32 v59, v171
	global_load_dwordx2 v[28:29], v[8:9], off offset:64
	global_load_dwordx2 v[26:27], v[8:9], off
	v_lshl_add_u64 v[8:9], s[94:95], 0, v[58:59]
	v_lshl_add_u64 v[8:9], v[8:9], 0, s[74:75]
	v_lshl_add_u64 v[8:9], v[8:9], 0, v[4:5]
	global_load_dwordx2 v[32:33], v[8:9], off offset:64
	global_load_dwordx2 v[30:31], v[8:9], off
	v_lshl_add_u64 v[8:9], s[6:7], 0, v[58:59]
	v_lshrrev_b32_e32 v21, 5, v20
	v_lshl_add_u64 v[8:9], v[8:9], 0, s[74:75]
	v_lshlrev_b32_e32 v7, 1, v19
	v_lshrrev_b32_e32 v10, 2, v19
	v_lshlrev_b32_e32 v66, 2, v21
	v_lshl_add_u64 v[8:9], v[8:9], 0, v[4:5]
	v_and_b32_e32 v7, 32, v7
	global_load_dwordx2 v[36:37], v[8:9], off offset:64
	global_load_dwordx2 v[34:35], v[8:9], off
	v_and_or_b32 v8, v10, 3, v66
	v_add_u32_e32 v7, 0, v7
	v_lshlrev_b32_e32 v8, 6, v8
	v_or_b32_e32 v60, 0x8000, v170
	v_mov_b32_e32 v61, v171
	v_add3_u32 v180, v7, v6, v8
	v_lshl_add_u64 v[6:7], s[94:95], 0, v[60:61]
	v_and_or_b32 v67, s5, 32, v175
	s_and_b32 s5, s3, 0x3fffffc0
	v_lshl_add_u64 v[6:7], v[6:7], 0, s[74:75]
	v_writelane_b32 v237, s0, 11
	s_lshl_b32 s0, s4, 2
	s_lshl_b32 s4, s5, 2
	v_lshl_add_u64 v[6:7], v[6:7], 0, v[4:5]
	v_lshl_add_u64 v[10:11], s[6:7], 0, v[60:61]
	s_add_i32 s78, s4, 0
	v_readlane_b32 s4, v242, 22
	global_load_dwordx2 v[40:41], v[6:7], off offset:64
	global_load_dwordx2 v[38:39], v[6:7], off
	v_lshl_add_u64 v[10:11], v[10:11], 0, s[74:75]
	v_readlane_b32 s5, v242, 23
	v_lshl_add_u64 v[10:11], v[10:11], 0, v[4:5]
	v_readlane_b32 s8, v242, 45
	v_lshl_add_u64 v[2:3], s[4:5], 0, v[2:3]
	v_readlane_b32 s4, v242, 43
	global_load_dwordx2 v[44:45], v[10:11], off offset:64
	global_load_dwordx2 v[42:43], v[10:11], off
	v_mov_b32_e32 v173, v5
	v_lshlrev_b32_e32 v172, 4, v21
	v_lshl_add_u64 v[2:3], v[2:3], 0, s[74:75]
	v_or_b32_e32 v62, 0xc000, v170
	v_mov_b32_e32 v63, v171
	v_readlane_b32 s5, v242, 44
	v_readlane_b32 s9, v242, 46
	s_mov_b32 s1, s87
	v_lshl_add_u64 v[6:7], s[4:5], 0, v[170:171]
	v_lshl_add_u64 v[8:9], s[8:9], 0, v[170:171]
	v_lshl_add_u64 v[2:3], v[2:3], 0, v[172:173]
	v_lshl_add_u64 v[46:47], s[94:95], 0, v[62:63]
	v_lshl_add_u64 v[48:49], s[6:7], 0, v[62:63]
	v_lshl_add_u64 v[54:55], v[6:7], 0, s[0:1]
	v_lshl_add_u64 v[56:57], v[8:9], 0, s[0:1]
	global_load_dwordx4 v[6:9], v[2:3], off
	global_load_dwordx4 v[10:13], v[2:3], off offset:32
	global_load_dwordx4 v[14:17], v[2:3], off offset:64
	global_load_dwordx4 v[116:119], v[2:3], off offset:96
	v_lshl_add_u64 v[2:3], v[46:47], 0, s[74:75]
	v_lshl_add_u64 v[46:47], v[48:49], 0, s[74:75]
	v_lshl_add_u64 v[2:3], v[2:3], 0, v[4:5]
	v_lshl_add_u64 v[50:51], v[46:47], 0, v[4:5]
	global_load_dwordx2 v[48:49], v[2:3], off offset:64
	global_load_dwordx2 v[46:47], v[2:3], off
	s_nop 0
	global_load_dwordx2 v[52:53], v[50:51], off offset:64
	global_load_dwordx2 v[50:51], v[50:51], off
	v_lshlrev_b32_e32 v4, 1, v174
	v_lshl_add_u64 v[2:3], v[54:55], 0, v[4:5]
	v_lshl_add_u64 v[64:65], v[56:57], 0, v[4:5]
	s_add_i32 s78, s78, 0x1a000
	v_cmp_lt_u32_e64 s[12:13], v66, v67
	v_cmp_gt_u32_e64 s[6:7], 32, v20
	v_lshlrev_b32_e32 v173, 10, v21
	v_lshlrev_b32_e32 v188, 4, v175
	v_cndmask_b32_e64 v122, 0, v185, s[6:7]
	v_cndmask_b32_e64 v121, 0, -1.0, s[6:7]
	v_mov_b32_e32 v120, v5
	v_mov_b32_e32 v123, v5
	v_lshl_add_u32 v182, v175, 2, s78
	v_mov_b32_e32 v156, v5
	s_waitcnt vmcnt(0)
; #define LAS __attribute__((address_space(3)))
; __device__ __forceinline__ float bflo(unsigned w) { return __uint_as_float(w << 16); }
; __device__ __forceinline__ float bfhi(unsigned w) { return __uint_as_float(w & 0xffff0000u); }
; __device__ __forceinline__ unsigned cvtpk(float lo, float hi) { f32x2 v = {lo, hi}; bf16x2_t b = __builtin_convertvector(v, bf16x2_t); return __builtin_bit_cast(unsigned, b); }
; __device__ __forceinline__ float bf_hi_part(float x) { return __uint_as_float(cvtpk(x, 0.f) << 16); }
; template <int TYPE>
; __device__ __forceinline__ void conv_store(const ConvRegs& c, const Args& a, int l, int h, size_t rowq, int lane) {
; #pragma unroll
;     for (int i = 0; i < 4; ++i) { const size_t grow = rowq + i * 8 + (lane >> 3);
;         float* ko = a.out + (TYPE == 0 ? O_FKP : O_SKP) + ((size_t)l * MP + grow) * W + h * HD + (lane & 7) * 8;
;         float* vo = a.out + (TYPE == 0 ? O_FVP : O_SVP) + ((size_t)l * MP + grow) * W + h * HD + (lane & 7) * 8;
;         const u32x4 kw = c.k[i], vw = c.v[i];
;         __builtin_nontemporal_store((f32x4){bflo(kw.x), bfhi(kw.x), bflo(kw.y), bfhi(kw.y)}, (f32x4*)ko); __builtin_nontemporal_store((f32x4){bflo(kw.z), bfhi(kw.z), bflo(kw.w), bfhi(kw.w)}, (f32x4*)(ko + 4));
;         __builtin_nontemporal_store((f32x4){bflo(vw.x), bfhi(vw.x), bflo(vw.y), bfhi(vw.y)}, (f32x4*)vo); __builtin_nontemporal_store((f32x4){bflo(vw.z), bfhi(vw.z), bflo(vw.w), bfhi(vw.w)}, (f32x4*)(vo + 4)); }
; }
; __device__ __forceinline__ void prompt_unit_fox(const Args& a, int l, int b, int h, int qb, LAS unsigned char* lds) {
;     ...
;     { const int idx = tid * 4; if (idx < q0 + 256) { const f32x4 c = *(const f32x4*)((const float*)(a.ws + WS_CKP) + (size_t)(b * 8 + h) * T + idx); *(LAS f32x4*)(lds + F_CK + idx * 4) = c;
; #pragma unroll
;         for (int e = 0; e < 4; ++e) { const float h1 = bf_hi_part(c[e]), r1 = c[e] - h1, h2 = bf_hi_part(r1), r2 = r1 - h2; ((LAS u32x2*)(lds + F_AUG))[idx + e] = (u32x2){cvtpk(h1, h2), cvtpk(r2, -1.0f)}; } } }
	s_cmp_lg_u32 s83, 0
	s_cbranch_scc0 .Lck_skip_l0
	ds_write_b128 v85, v[92:95]
	v_cvt_pk_bf16_f32 v85, v92, 0
	v_cvt_pk_bf16_f32 v87, v93, 0
	v_cvt_pk_bf16_f32 v88, v94, 0
	v_cvt_pk_bf16_f32 v91, v95, 0
	v_lshlrev_b32_e32 v85, 16, v85
	v_lshlrev_b32_e32 v87, 16, v87
	v_lshlrev_b32_e32 v88, 16, v88
	v_lshlrev_b32_e32 v91, 16, v91
	v_sub_f32_e32 v92, v92, v85
	v_sub_f32_e32 v93, v93, v87
	v_sub_f32_e32 v96, v94, v88
	v_sub_f32_e32 v95, v95, v91
	v_cvt_pk_bf16_f32 v94, v92, 0
	v_cvt_pk_bf16_f32 v97, v93, 0
	v_cvt_pk_bf16_f32 v98, v96, 0
	v_cvt_pk_bf16_f32 v99, v95, 0
	v_lshlrev_b32_e32 v94, 16, v94
	v_lshlrev_b32_e32 v97, 16, v97
	v_lshlrev_b32_e32 v98, 16, v98
	v_lshlrev_b32_e32 v99, 16, v99
	v_sub_f32_e32 v100, v92, v94
	v_cvt_pk_bf16_f32 v92, v85, v94
	v_sub_f32_e32 v85, v93, v97
	v_cvt_pk_bf16_f32 v94, v87, v97
	v_sub_f32_e32 v87, v96, v98
	v_cvt_pk_bf16_f32 v96, v88, v98
	v_sub_f32_e32 v88, v95, v99
	v_cvt_pk_bf16_f32 v93, v100, -1.0
	v_cvt_pk_bf16_f32 v95, v85, -1.0
	v_cvt_pk_bf16_f32 v98, v91, v99
	v_cvt_pk_bf16_f32 v97, v87, -1.0
	v_cvt_pk_bf16_f32 v99, v88, -1.0
	ds_write_b128 v86, v[92:95]
	ds_write_b128 v86, v[96:99] offset:16
.Lck_skip_l0:
	v_lshlrev_b32_e32 v54, 16, v22
	v_and_b32_e32 v55, 0xffff0000, v22
	v_lshlrev_b32_e32 v56, 16, v23
	v_and_b32_e32 v57, 0xffff0000, v23
	v_lshlrev_b32_e32 v22, 16, v24
	v_and_b32_e32 v23, 0xffff0000, v24
	v_lshlrev_b32_e32 v24, 16, v25
	v_and_b32_e32 v25, 0xffff0000, v25
	global_store_dwordx4 v[2:3], v[22:25], off offset:128
	global_store_dwordx4 v[2:3], v[54:57], off
	v_lshl_add_u64 v[2:3], s[4:5], 0, v[58:59]
	v_lshlrev_b32_e32 v22, 16, v26
	v_and_b32_e32 v23, 0xffff0000, v26
	v_lshlrev_b32_e32 v24, 16, v27
	v_and_b32_e32 v25, 0xffff0000, v27
	global_store_dwordx4 v[64:65], v[22:25], off
	v_lshl_add_u64 v[2:3], v[2:3], 0, s[0:1]
	v_lshl_add_u64 v[2:3], v[2:3], 0, v[4:5]
	v_lshlrev_b32_e32 v22, 16, v28
	v_and_b32_e32 v23, 0xffff0000, v28
	v_lshlrev_b32_e32 v24, 16, v29
	v_and_b32_e32 v25, 0xffff0000, v29
	global_store_dwordx4 v[64:65], v[22:25], off offset:128
	v_mov_b32_e32 v54, v5
	v_mov_b32_e32 v55, v5
	v_lshl_add_u64 v[22:23], s[8:9], 0, v[58:59]
	v_lshl_add_u64 v[22:23], v[22:23], 0, s[0:1]
	v_lshl_add_u64 v[26:27], v[22:23], 0, v[4:5]
	v_lshlrev_b32_e32 v22, 16, v30
	v_and_b32_e32 v23, 0xffff0000, v30
	v_lshlrev_b32_e32 v24, 16, v31
	v_and_b32_e32 v25, 0xffff0000, v31
	global_store_dwordx4 v[2:3], v[22:25], off
	v_mov_b32_e32 v56, v5
	v_mov_b32_e32 v57, v5
	v_lshlrev_b32_e32 v22, 16, v32
	v_and_b32_e32 v23, 0xffff0000, v32
	v_lshlrev_b32_e32 v24, 16, v33
	v_and_b32_e32 v25, 0xffff0000, v33
	global_store_dwordx4 v[2:3], v[22:25], off offset:128
	v_lshl_add_u64 v[2:3], s[4:5], 0, v[60:61]
	v_lshl_add_u64 v[2:3], v[2:3], 0, s[0:1]
	v_lshlrev_b32_e32 v22, 16, v34
	v_and_b32_e32 v23, 0xffff0000, v34
	v_lshlrev_b32_e32 v24, 16, v35
	v_and_b32_e32 v25, 0xffff0000, v35
	global_store_dwordx4 v[26:27], v[22:25], off
	v_lshl_add_u64 v[2:3], v[2:3], 0, v[4:5]
	v_mov_b32_e32 v58, v5
	v_lshlrev_b32_e32 v22, 16, v36
	v_and_b32_e32 v23, 0xffff0000, v36
	v_lshlrev_b32_e32 v24, 16, v37
	v_and_b32_e32 v25, 0xffff0000, v37
	global_store_dwordx4 v[26:27], v[22:25], off offset:128
	v_mov_b32_e32 v59, v5
	v_mov_b32_e32 v64, v5
	v_lshl_add_u64 v[22:23], s[8:9], 0, v[60:61]
	v_lshl_add_u64 v[22:23], v[22:23], 0, s[0:1]
	v_lshl_add_u64 v[26:27], v[22:23], 0, v[4:5]
	v_lshlrev_b32_e32 v22, 16, v38
	v_and_b32_e32 v23, 0xffff0000, v38
	v_lshlrev_b32_e32 v24, 16, v39
	v_and_b32_e32 v25, 0xffff0000, v39
	global_store_dwordx4 v[2:3], v[22:25], off
	v_mov_b32_e32 v60, v5
	v_mov_b32_e32 v61, v5
	v_lshlrev_b32_e32 v22, 16, v40
	v_and_b32_e32 v23, 0xffff0000, v40
	v_lshlrev_b32_e32 v24, 16, v41
	v_and_b32_e32 v25, 0xffff0000, v41
	global_store_dwordx4 v[2:3], v[22:25], off offset:128
	v_lshl_add_u64 v[2:3], s[4:5], 0, v[62:63]
	v_lshl_add_u64 v[2:3], v[2:3], 0, s[0:1]
	v_lshlrev_b32_e32 v22, 16, v42
	v_and_b32_e32 v23, 0xffff0000, v42
	v_lshlrev_b32_e32 v24, 16, v43
	v_and_b32_e32 v25, 0xffff0000, v43
	global_store_dwordx4 v[26:27], v[22:25], off
	v_lshl_add_u64 v[2:3], v[2:3], 0, v[4:5]
	v_mov_b32_e32 v65, v5
	v_lshlrev_b32_e32 v22, 16, v44
	v_and_b32_e32 v23, 0xffff0000, v44
	v_lshlrev_b32_e32 v24, 16, v45
	v_and_b32_e32 v25, 0xffff0000, v45
	global_store_dwordx4 v[26:27], v[22:25], off offset:128
	v_mov_b32_e32 v157, v5
	v_mov_b32_e32 v158, v5
	v_lshl_add_u64 v[22:23], s[8:9], 0, v[62:63]
	v_lshl_add_u64 v[22:23], v[22:23], 0, s[0:1]
	v_lshl_add_u64 v[26:27], v[22:23], 0, v[4:5]
	v_lshlrev_b32_e32 v22, 16, v46
	v_and_b32_e32 v23, 0xffff0000, v46
; #define LAS __attribute__((address_space(3)))
; __device__ __forceinline__ int crow(int r, int hi) { return (r & 3) + 8 * (r >> 2) + 4 * hi; }
; #define ATT_WAIT_BAR() asm volatile("s_waitcnt vmcnt(0) lgkmcnt(0)\n\ts_barrier" ::: "memory")
;     ...
;     if (masked) {
;         asm volatile("; masked tile" ::: "memory");
; #pragma unroll
;         for (int r = 0; r < 16; ++r) { const int kv = crow(r, hi); if (kv >= qlim) p0[r] = NEG; if (kv + 32 >= qlim) p1[r] = NEG; }
; __device__ __forceinline__ void prompt_unit_fox(const Args& a, int l, int b, int h, int qb, LAS unsigned char* lds) {
;     ...
;     const lds_cptr vp0 = (lds_cptr)lds + F_V + ((lane >> 4) & 1) * 32 + (lane & 3) * 8 + (4 * hi + ((lane & 15) >> 2)) * 64;
;     const int ql = 32 * (wid & 1) + r32, qlim = ql + 1;
;     LAS float* wsf = (LAS float*)(lds + F_WSF) + wid * 64;
;     FoxState st; st.m = 0.f; st.l = 0.f; st.mq = (bf16x8){}; st.o[0] = (f32x16){}; st.o[1] = (f32x16){};
;     PairP pp; bool pending = false;
; #pragma unroll
;     for (int i = 0; i < 8; ++i) pp.w[i] = (u32x4){0u, 0u, 0u, 0u};
;     { ConvRegs cv; conv_load(cv, a, rowb + q0 + wid * 32, col, lane); conv_store<0>(cv, a, l, h, rowb + q0 + wid * 32, lane); }
;     int slot = 0, pslot = 0;
;     ...
;         ATT_WAIT_BAR();
	v_lshlrev_b32_e32 v24, 16, v47
	v_and_b32_e32 v25, 0xffff0000, v47
	global_store_dwordx4 v[2:3], v[22:25], off
	s_add_i32 s1, 0, 0x18000
	v_add_u32_e32 v184, s1, v172
	v_lshlrev_b32_e32 v22, 16, v48
	v_and_b32_e32 v23, 0xffff0000, v48
	v_lshlrev_b32_e32 v24, 16, v49
	v_and_b32_e32 v25, 0xffff0000, v49
	global_store_dwordx4 v[2:3], v[22:25], off offset:128
	v_or_b32_e32 v2, 32, v66
	v_cmp_gt_u32_e64 s[10:11], v2, v67
	v_or_b32_e32 v2, 33, v66
	v_cmp_gt_u32_e64 s[14:15], v2, v67
	v_or_b32_e32 v2, 2, v66
	v_cmp_gt_u32_e64 s[16:17], v2, v67
	v_or_b32_e32 v2, 34, v66
	v_cmp_gt_u32_e64 s[18:19], v2, v67
	v_or_b32_e32 v2, 3, v66
	v_cmp_gt_u32_e64 s[20:21], v2, v67
	v_or_b32_e32 v2, 35, v66
	v_cmp_gt_u32_e64 s[22:23], v2, v67
	v_or_b32_e32 v2, 8, v66
	v_cmp_gt_u32_e64 s[24:25], v2, v67
	v_or_b32_e32 v2, 40, v66
	v_cmp_gt_u32_e64 s[26:27], v2, v67
	v_or_b32_e32 v2, 9, v66
	v_cmp_gt_u32_e64 s[28:29], v2, v67
	v_or_b32_e32 v2, 41, v66
	v_cmp_gt_u32_e64 s[30:31], v2, v67
	v_or_b32_e32 v2, 10, v66
	v_cmp_gt_u32_e64 s[34:35], v2, v67
	v_or_b32_e32 v2, 42, v66
	v_cmp_gt_u32_e64 s[36:37], v2, v67
	v_or_b32_e32 v2, 11, v66
	v_cmp_gt_u32_e64 s[38:39], v2, v67
	v_or_b32_e32 v2, 43, v66
	v_cmp_gt_u32_e64 s[40:41], v2, v67
	v_or_b32_e32 v2, 16, v66
	v_cmp_gt_u32_e64 s[42:43], v2, v67
	v_or_b32_e32 v2, 48, v66
	v_cmp_gt_u32_e64 s[44:45], v2, v67
	v_or_b32_e32 v2, 17, v66
	v_cmp_gt_u32_e64 s[46:47], v2, v67
	v_or_b32_e32 v2, 49, v66
	v_cmp_gt_u32_e64 s[48:49], v2, v67
	v_or_b32_e32 v2, 18, v66
	v_cmp_gt_u32_e64 s[50:51], v2, v67
	v_or_b32_e32 v2, 50, v66
	v_cmp_gt_u32_e64 s[52:53], v2, v67
	v_or_b32_e32 v2, 19, v66
	v_cmp_gt_u32_e64 s[54:55], v2, v67
	v_or_b32_e32 v2, 51, v66
	v_cmp_gt_u32_e64 s[56:57], v2, v67
	v_or_b32_e32 v2, 24, v66
	v_cmp_gt_u32_e64 s[58:59], v2, v67
	v_or_b32_e32 v2, 56, v66
	v_cmp_gt_u32_e64 s[60:61], v2, v67
	v_or_b32_e32 v2, 25, v66
	v_cmp_gt_u32_e64 s[62:63], v2, v67
	v_or_b32_e32 v2, 57, v66
	v_cmp_gt_u32_e64 s[64:65], v2, v67
	v_or_b32_e32 v2, 26, v66
	v_cmp_gt_u32_e64 s[66:67], v2, v67
	v_or_b32_e32 v2, 58, v66
	v_cmp_gt_u32_e64 s[68:69], v2, v67
	v_or_b32_e32 v2, 27, v66
	v_cmp_gt_u32_e64 s[70:71], v2, v67
	v_or_b32_e32 v2, 59, v66
	v_lshlrev_b32_e32 v22, 16, v50
	v_and_b32_e32 v23, 0xffff0000, v50
	v_lshlrev_b32_e32 v24, 16, v51
	v_and_b32_e32 v25, 0xffff0000, v51
	s_add_i32 s1, 0, 0x1a800
	v_cmp_gt_u32_e64 s[8:9], v66, v67
	v_cmp_gt_u32_e64 s[72:73], v2, v67
	v_mov_b32_e32 v66, v5
	v_mov_b32_e32 v67, v5
	global_store_dwordx4 v[26:27], v[22:25], off
	s_bitcmp1_b32 s3, 7
	v_mov_b32_e32 v62, v5
	v_lshlrev_b32_e32 v22, 16, v52
	v_and_b32_e32 v23, 0xffff0000, v52
	v_lshlrev_b32_e32 v24, 16, v53
	v_and_b32_e32 v25, 0xffff0000, v53
	v_mov_b32_e32 v52, v5
	v_mov_b32_e32 v53, v5
	v_mov_b32_e32 v63, v5
	v_mov_b64_e32 v[82:83], v[66:67]
	v_lshl_add_u32 v186, v175, 3, s1
	s_cselect_b64 s[94:95], -1, 0
	s_mov_b32 s1, 0
	v_mov_b32_e32 v159, v5
	v_mov_b32_e32 v192, 0
	v_mov_b32_e32 v124, 0
	v_mov_b32_e32 v125, 0
	v_mov_b32_e32 v126, 0
	v_mov_b32_e32 v127, 0
	v_mov_b32_e32 v128, 0
	v_mov_b32_e32 v129, 0
	v_mov_b32_e32 v130, 0
	v_mov_b32_e32 v131, 0
	v_mov_b32_e32 v132, 0
	v_mov_b32_e32 v133, 0
	v_mov_b32_e32 v134, 0
	v_mov_b32_e32 v135, 0
	v_mov_b32_e32 v136, 0
	v_mov_b32_e32 v137, 0
	v_mov_b32_e32 v138, 0
	v_mov_b32_e32 v139, 0
	v_mov_b32_e32 v140, 0
	v_mov_b32_e32 v141, 0
	v_mov_b32_e32 v142, 0
	v_mov_b32_e32 v143, 0
	v_mov_b32_e32 v144, 0
	v_mov_b32_e32 v145, 0
	v_mov_b32_e32 v146, 0
	v_mov_b32_e32 v147, 0
	v_mov_b32_e32 v148, 0
	v_mov_b32_e32 v149, 0
	v_mov_b32_e32 v150, 0
	v_mov_b32_e32 v151, 0
	v_mov_b32_e32 v152, 0
	v_mov_b32_e32 v153, 0
	v_mov_b32_e32 v154, 0
	v_mov_b32_e32 v155, 0
	v_cndmask_b32_e64 v2, 0, v187, s[6:7]
	s_mov_b32 s75, 0
	v_mov_b64_e32 v[80:81], v[64:65]
	v_mov_b64_e32 v[78:79], v[62:63]
	v_mov_b64_e32 v[76:77], v[60:61]
	v_mov_b64_e32 v[74:75], v[58:59]
	v_mov_b64_e32 v[72:73], v[56:57]
	v_mov_b64_e32 v[70:71], v[54:55]
	v_mov_b64_e32 v[68:69], v[52:53]
	v_mov_b32_e32 v193, 0
	s_mov_b64 s[4:5], 0
	global_store_dwordx4 v[26:27], v[22:25], off offset:128
	s_waitcnt vmcnt(16) lgkmcnt(0)
	s_barrier
	v_mov_b64_e32 v[20:21], 0
	v_mov_b64_e32 v[22:23], 0
	v_mov_b64_e32 v[24:25], 0
	v_mov_b64_e32 v[26:27], 0
	v_mov_b64_e32 v[28:29], 0
	v_mov_b64_e32 v[30:31], 0
	v_mov_b64_e32 v[32:33], 0
	v_mov_b64_e32 v[34:35], 0
	v_mov_b64_e32 v[36:37], 0
	v_mov_b64_e32 v[38:39], 0
	v_mov_b64_e32 v[40:41], 0
	v_mov_b64_e32 v[42:43], 0
	v_mov_b64_e32 v[44:45], 0
	v_mov_b64_e32 v[46:47], 0
	v_mov_b64_e32 v[48:49], 0
	v_mov_b64_e32 v[50:51], 0
	s_branch .Lfox_top_l0

; #define LAS __attribute__((address_space(3)))
; __device__ __forceinline__ unsigned cvtpk(float lo, float hi) { f32x2 v = {lo, hi}; bf16x2_t b = __builtin_convertvector(v, bf16x2_t); return __builtin_bit_cast(unsigned, b); }
; __device__ __forceinline__ float bf_hi_part(float x) { return __uint_as_float(cvtpk(x, 0.f) << 16); }
; __device__ __forceinline__ void prompt_unit_fox(const Args& a, int l, int b, int h, int qb, LAS unsigned char* lds) {
;     ...
;     ATT_DMA2(NP - 1, 0);
;     { const int idx = tid * 4; if (idx < q0 + 256) { const f32x4 c = *(const f32x4*)((const float*)(a.ws + WS_CKP) + (size_t)(b * 8 + h) * T + idx); *(LAS f32x4*)(lds + F_CK + idx * 4) = c;
; #pragma unroll
;         for (int e = 0; e < 4; ++e) { const float h1 = bf_hi_part(c[e]), r1 = c[e] - h1, h2 = bf_hi_part(r1), r2 = r1 - h2; ((LAS u32x2*)(lds + F_AUG))[idx + e] = (u32x2){cvtpk(h1, h2), cvtpk(r2, -1.0f)}; } } }
;     bf16x8 qr[4];
;     { const bf16* Qw = (const bf16*)(a.ws + WS_Q) + (rowb + q0 + wid * 32 + r32) * D + col;
; #pragma unroll
;       for (int d0 = 0; d0 < 4; ++d0) qr[d0] = *(const bf16x8*)(Qw + d0 * 16 + hi * 8); }
;     const lds_cptr vp0 = (lds_cptr)lds + F_V + ((lane >> 4) & 1) * 32 + (lane & 3) * 8 + (4 * hi + ((lane & 15) >> 2)) * 64;
;     const int ql = 32 * (wid & 1) + r32, qlim = ql + 1;
;     LAS float* wsf = (LAS float*)(lds + F_WSF) + wid * 64;
;     FoxState st; st.m = 0.f; st.l = 0.f; st.mq = (bf16x8){}; st.o[0] = (f32x16){}; st.o[1] = (f32x16){};
;     PairP pp; bool pending = false;
; #pragma unroll
;     for (int i = 0; i < 8; ++i) pp.w[i] = (u32x4){0u, 0u, 0u, 0u};
;     { ConvRegs cv; conv_load(cv, a, rowb + q0 + wid * 32, col, lane); conv_store<0>(cv, a, l, h, rowb + q0 + wid * 32, lane); }
.LBB0_960:
	s_and_b64 vcc, exec, s[2:3]
	s_cbranch_vccz .LBB0_1009
	s_lshr_b32 s8, s0, 6
	s_bfe_u32 s16, s0, 0x30003
	s_andn2_b32 s0, 7, s0
	v_mov_b32_e32 v19, v0
	s_lshl_b32 s9, s0, 8
	s_add_i32 s12, s9, 0x100
	v_readfirstlane_b32 s6, v19
	s_ashr_i32 s1, s6, 6
	s_lshr_b32 s13, s12, 7
	s_lshl_b32 s7, s16, 6
	s_lshl_b32 s10, s8, 22
	v_readlane_b32 s2, v242, 20
	v_readlane_b32 s3, v242, 21
	s_add_u32 s2, s2, s10
	s_addc_u32 s3, s3, 0
	s_lshl_b32 s11, s16, 7
	s_add_u32 s2, s2, s11
	s_addc_u32 s3, s3, 0
	v_readlane_b32 s14, v242, 22
	v_readlane_b32 s15, v242, 23
	s_add_u32 s10, s14, s10
	v_and_b32_e32 v20, 63, v19
	s_addc_u32 s14, s15, 0
	s_add_u32 s10, s10, s11
	v_lshlrev_b32_e32 v4, 11, v20
	s_addc_u32 s11, s14, 0
	v_lshl_add_u64 v[2:3], s[2:3], 0, v[4:5]
	s_lshl_b32 s2, s1, 3
	s_ashr_i32 s3, s2, 31
	v_lshl_add_u64 v[170:171], s[2:3], 1, v[2:3]
	s_lshl_b32 s2, s1, 4
	v_bfe_u32 v1, v19, 2, 4
	v_and_or_b32 v1, s2, 48, v1
	s_ashr_i32 s2, s6, 3
	v_lshlrev_b32_e32 v4, 11, v1
	s_andn2_b32 s2, s2, 31
	v_lshlrev_b32_e32 v1, 3, v19
	v_lshl_add_u64 v[2:3], s[10:11], 0, v[4:5]
	s_ashr_i32 s3, s2, 31
	v_and_b32_e32 v1, 24, v1
	s_add_i32 s78, s13, -1
	s_mov_b32 s79, s87
	v_lshl_add_u64 v[2:3], s[2:3], 1, v[2:3]
	v_lshlrev_b32_e32 v4, 1, v1
	s_lshl_b64 s[2:3], s[78:79], 18
	s_lshl_b32 s96, s1, 10
	v_lshl_add_u64 v[172:173], v[2:3], 0, v[4:5]
	v_lshl_add_u64 v[2:3], v[170:171], 0, s[2:3]
	s_add_i32 s96, s96, 0
	s_mov_b32 s10, m0
	s_mov_b32 m0, s96
	s_nop 0
	global_load_lds_dwordx4 v[2:3], off
	s_mov_b32 m0, s10
	s_mov_b64 s[14:15], 0x20000
	v_lshl_add_u64 v[2:3], v[2:3], 0, s[14:15]
	s_add_i32 s97, s96, 0x2000
	s_mov_b32 s10, m0
	s_mov_b32 m0, s97
	s_nop 0
	global_load_lds_dwordx4 v[2:3], off
	s_mov_b32 m0, s10
	v_lshl_add_u64 v[2:3], v[172:173], 0, s[2:3]
	s_add_i32 s84, s96, 0xc000
	s_mov_b32 s2, m0
	s_mov_b32 m0, s84
	s_nop 0
	global_load_lds_dwordx4 v[2:3], off
	s_mov_b32 m0, s2
	v_lshl_add_u64 v[2:3], v[2:3], 0, s[14:15]
	s_add_i32 s85, s96, 0xe000
	s_mov_b32 s2, m0
	s_mov_b32 m0, s85
	s_nop 0
	global_load_lds_dwordx4 v[2:3], off
	s_mov_b32 m0, s2
	v_lshlrev_b32_e32 v2, 2, v19
	v_cmp_gt_i32_e32 vcc, s12, v2
	s_mov_b32 s83, vcc_lo
	s_and_saveexec_b64 s[2:3], vcc
	s_cbranch_execz .LBB0_963
	s_lshl_b32 s10, s8, 14
	s_lshl_b32 s11, s16, 11
	s_or_b32 s10, s11, s10
	s_mov_b32 s11, s87
	s_lshl_b64 s[10:11], s[10:11], 2
	v_readlane_b32 s12, v237, 2
	s_add_u32 s10, s12, s10
	v_readlane_b32 s12, v242, 40
	s_addc_u32 s11, s12, s11
	v_ashrrev_i32_e32 v3, 31, v2
	v_lshl_add_u64 v[6:7], v[2:3], 2, s[10:11]
	global_load_dwordx4 v[90:93], v[6:7], off
	v_lshl_add_u32 v87, v19, 4, 0
	v_add_u32_e32 v87, 0x18000, v87
	v_lshl_add_u32 v86, v2, 3, 0
	v_add_u32_e32 v86, 0x1a800, v86
.LBB0_963:
	v_writelane_b32 v242, s16, 32
	s_or_b64 exec, exec, s[2:3]
	s_lshl_b32 s0, s0, 2
	s_ashr_i32 s2, s6, 7
	s_add_i32 s2, s2, s0
	s_ashr_i32 s0, s2, 1
	s_cmp_lt_i32 s1, 4
	s_cselect_b64 s[90:91], -1, 0
	s_lshl_b32 s2, s8, 11
	s_lshl_b32 s3, s1, 5
	s_or_b32 s2, s9, s2
	s_ashr_i32 s8, s3, 31
	s_add_u32 s79, s3, s2
	v_and_b32_e32 v180, 31, v19
	s_addc_u32 s10, s8, 0
	v_or_b32_e32 v168, s79, v180
	v_mov_b32_e32 v169, s10
	v_readlane_b32 s8, v242, 28
	v_lshlrev_b64 v[2:3], 11, v[168:169]
	v_readlane_b32 s9, v242, 29
	v_lshrrev_b32_e32 v21, 5, v20
	s_lshl_b32 s74, s7, 1
	v_lshl_add_u64 v[2:3], s[8:9], 0, v[2:3]
	s_mov_b32 s75, s87
	v_lshl_add_u64 v[2:3], v[2:3], 0, s[74:75]
	v_lshlrev_b32_e32 v174, 4, v21
	v_mov_b32_e32 v175, v5
	v_lshl_add_u64 v[2:3], v[2:3], 0, v[174:175]
	global_load_dwordx4 v[6:9], v[2:3], off
	global_load_dwordx4 v[10:13], v[2:3], off offset:32
	global_load_dwordx4 v[14:17], v[2:3], off offset:64
	global_load_dwordx4 v[116:119], v[2:3], off offset:96
	v_lshlrev_b32_e32 v2, 1, v19
	v_and_b32_e32 v2, 32, v2
	v_add_u32_e32 v3, 0, v2
	v_lshlrev_b32_e32 v2, 2, v21
	v_lshrrev_b32_e32 v4, 2, v19
	v_and_or_b32 v4, v4, 3, v2
	v_lshlrev_b32_e32 v4, 6, v4
	s_and_b32 s2, s6, 0x3fffffc0
	v_add3_u32 v175, v3, v1, v4
	s_lshl_b32 s2, s2, 2
	v_lshrrev_b32_e32 v1, 3, v20
	v_and_or_b32 v3, s3, 32, v180
	s_add_i32 s89, s2, 0
	v_or_b32_e32 v168, s79, v1
	v_readlane_b32 s2, v242, 20
	v_lshlrev_b32_e32 v4, 3, v20
	v_lshlrev_b64 v[176:177], 11, v[168:169]
	v_readlane_b32 s3, v242, 21
	v_readlane_b32 s8, v242, 22
	v_and_b32_e32 v178, 56, v4
	v_lshl_add_u64 v[22:23], s[2:3], 0, v[176:177]
	v_readlane_b32 s9, v242, 23
	v_lshl_add_u64 v[22:23], v[22:23], 0, s[74:75]
	v_mov_b32_e32 v4, v178
	v_lshl_add_u64 v[26:27], s[8:9], 0, v[176:177]
	v_lshl_add_u64 v[22:23], v[22:23], 0, v[4:5]
	v_lshl_add_u64 v[26:27], v[26:27], 0, s[74:75]
	v_or_b32_e32 v34, 0x4000, v176
	v_mov_b32_e32 v35, v177
	global_load_dwordx2 v[24:25], v[22:23], off offset:64
	global_load_dwordx2 v[22:23], v[22:23], off
	v_lshl_add_u64 v[26:27], v[26:27], 0, v[4:5]
	v_lshl_add_u64 v[30:31], s[2:3], 0, v[34:35]
	global_load_dwordx2 v[28:29], v[26:27], off offset:64
	global_load_dwordx2 v[26:27], v[26:27], off
	v_lshl_add_u64 v[30:31], v[30:31], 0, s[74:75]
	v_lshl_add_u64 v[30:31], v[30:31], 0, v[4:5]
	global_load_dwordx2 v[32:33], v[30:31], off offset:64
	global_load_dwordx2 v[30:31], v[30:31], off
	v_lshl_add_u64 v[34:35], s[8:9], 0, v[34:35]
	v_lshl_add_u64 v[34:35], v[34:35], 0, s[74:75]
	v_lshl_add_u64 v[34:35], v[34:35], 0, v[4:5]
	global_load_dwordx2 v[36:37], v[34:35], off offset:64
	global_load_dwordx2 v[34:35], v[34:35], off
	v_or_b32_e32 v42, 0x8000, v176
	v_mov_b32_e32 v43, v177
	v_lshl_add_u64 v[38:39], s[2:3], 0, v[42:43]
	v_lshl_add_u64 v[38:39], v[38:39], 0, s[74:75]
	v_lshl_add_u64 v[38:39], v[38:39], 0, v[4:5]
	global_load_dwordx2 v[40:41], v[38:39], off offset:64
	global_load_dwordx2 v[38:39], v[38:39], off
; #define LAS __attribute__((address_space(3)))
; __device__ __forceinline__ float bflo(unsigned w) { return __uint_as_float(w << 16); }
; __device__ __forceinline__ float bfhi(unsigned w) { return __uint_as_float(w & 0xffff0000u); }
; __device__ __forceinline__ unsigned cvtpk(float lo, float hi) { f32x2 v = {lo, hi}; bf16x2_t b = __builtin_convertvector(v, bf16x2_t); return __builtin_bit_cast(unsigned, b); }
; __device__ __forceinline__ void conv_load(ConvRegs& c, const Args& a, size_t rowq, int col, int lane) {
; #pragma unroll
;     for (int i = 0; i < 4; ++i) { const size_t grow = rowq + i * 8 + (lane >> 3);
;         c.k[i] = *(const u32x4*)((const bf16*)(a.ws + WS_K) + grow * D + col + (lane & 7) * 8); c.v[i] = *(const u32x4*)((const bf16*)(a.ws + WS_V) + grow * D + col + (lane & 7) * 8); }
; }
; template <int TYPE>
; __device__ __forceinline__ void conv_store(const ConvRegs& c, const Args& a, int l, int h, size_t rowq, int lane) {
; #pragma unroll
;     for (int i = 0; i < 4; ++i) { const size_t grow = rowq + i * 8 + (lane >> 3);
;         float* ko = a.out + (TYPE == 0 ? O_FKP : O_SKP) + ((size_t)l * MP + grow) * W + h * HD + (lane & 7) * 8;
;         float* vo = a.out + (TYPE == 0 ? O_FVP : O_SVP) + ((size_t)l * MP + grow) * W + h * HD + (lane & 7) * 8;
;         const u32x4 kw = c.k[i], vw = c.v[i];
;         __builtin_nontemporal_store((f32x4){bflo(kw.x), bfhi(kw.x), bflo(kw.y), bfhi(kw.y)}, (f32x4*)ko); __builtin_nontemporal_store((f32x4){bflo(kw.z), bfhi(kw.z), bflo(kw.w), bfhi(kw.w)}, (f32x4*)(ko + 4));
;         __builtin_nontemporal_store((f32x4){bflo(vw.x), bfhi(vw.x), bflo(vw.y), bfhi(vw.y)}, (f32x4*)vo); __builtin_nontemporal_store((f32x4){bflo(vw.z), bfhi(vw.z), bflo(vw.w), bfhi(vw.w)}, (f32x4*)(vo + 4)); }
; }
; __device__ __forceinline__ void prompt_unit_fox(const Args& a, int l, int b, int h, int qb, LAS unsigned char* lds) {
;     ...
;     { const int idx = tid * 4; if (idx < q0 + 256) { const f32x4 c = *(const f32x4*)((const float*)(a.ws + WS_CKP) + (size_t)(b * 8 + h) * T + idx); *(LAS f32x4*)(lds + F_CK + idx * 4) = c;
; #pragma unroll
;         for (int e = 0; e < 4; ++e) { const float h1 = bf_hi_part(c[e]), r1 = c[e] - h1, h2 = bf_hi_part(r1), r2 = r1 - h2; ((LAS u32x2*)(lds + F_AUG))[idx + e] = (u32x2){cvtpk(h1, h2), cvtpk(r2, -1.0f)}; } } }
	v_lshl_add_u64 v[42:43], s[8:9], 0, v[42:43]
	v_lshl_add_u64 v[42:43], v[42:43], 0, s[74:75]
	v_lshl_add_u64 v[42:43], v[42:43], 0, v[4:5]
	global_load_dwordx2 v[44:45], v[42:43], off offset:64
	global_load_dwordx2 v[42:43], v[42:43], off
	v_or_b32_e32 v50, 0xc000, v176
	v_mov_b32_e32 v51, v177
	v_lshl_add_u64 v[46:47], s[2:3], 0, v[50:51]
	v_lshl_add_u64 v[46:47], v[46:47], 0, s[74:75]
	v_lshl_add_u64 v[46:47], v[46:47], 0, v[4:5]
	global_load_dwordx2 v[48:49], v[46:47], off offset:64
	global_load_dwordx2 v[46:47], v[46:47], off
	v_lshl_add_u64 v[50:51], s[8:9], 0, v[50:51]
	v_lshl_add_u64 v[50:51], v[50:51], 0, s[74:75]
	v_lshl_add_u64 v[50:51], v[50:51], 0, v[4:5]
	global_load_dwordx2 v[52:53], v[50:51], off offset:64
	global_load_dwordx2 v[50:51], v[50:51], off
	s_add_i32 s89, s89, 0x1a000
	s_add_u32 s2, s79, 0x10000
	v_writelane_b32 v242, s10, 34
	s_addc_u32 s3, s10, 0
	v_or_b32_e32 v54, s2, v1
	v_mov_b32_e32 v55, s3
	v_readlane_b32 s2, v242, 26
	v_lshlrev_b64 v[54:55], 11, v[54:55]
	v_readlane_b32 s3, v242, 27
	s_lshl_b32 s92, s7, 2
	s_mov_b32 s93, s87
	v_lshl_add_u64 v[56:57], s[2:3], 0, v[54:55]
	v_readlane_b32 s2, v242, 43
	v_readlane_b32 s3, v242, 44
	v_lshl_add_u64 v[56:57], v[56:57], 0, s[92:93]
	v_lshlrev_b32_e32 v4, 1, v178
	v_lshl_add_u64 v[54:55], s[2:3], 0, v[54:55]
	v_lshl_add_u64 v[54:55], v[54:55], 0, s[92:93]
	v_lshl_add_u64 v[58:59], v[56:57], 0, v[4:5]
	v_lshl_add_u64 v[60:61], v[54:55], 0, v[4:5]
	v_or_b32_e32 v4, 32, v2
	v_cmp_gt_u32_e64 s[10:11], v4, v3
	v_or_b32_e32 v4, 33, v2
	v_cmp_gt_u32_e64 s[14:15], v4, v3
	v_or_b32_e32 v4, 2, v2
	v_cmp_gt_u32_e64 s[16:17], v4, v3
	v_or_b32_e32 v4, 34, v2
	v_cmp_gt_u32_e64 s[18:19], v4, v3
	v_or_b32_e32 v4, 3, v2
	v_cmp_gt_u32_e64 s[20:21], v4, v3
	v_or_b32_e32 v4, 35, v2
	v_cmp_gt_u32_e64 s[22:23], v4, v3
	v_or_b32_e32 v4, 8, v2
	s_mov_b64 s[2:3], 0x4000
	v_cmp_gt_u32_e64 s[24:25], v4, v3
	v_or_b32_e32 v4, 40, v2
	v_cmp_gt_u32_e64 s[26:27], v4, v3
	v_or_b32_e32 v4, 9, v2
	v_cmp_gt_u32_e64 s[28:29], v4, v3
	v_or_b32_e32 v4, 41, v2
	v_cmp_gt_u32_e64 s[30:31], v4, v3
	v_or_b32_e32 v4, 10, v2
	v_cmp_gt_u32_e64 s[34:35], v4, v3
	v_or_b32_e32 v4, 42, v2
	v_cmp_gt_u32_e64 s[36:37], v4, v3
	v_or_b32_e32 v4, 11, v2
	v_cmp_gt_u32_e64 s[38:39], v4, v3
	v_or_b32_e32 v4, 43, v2
	v_cmp_gt_u32_e64 s[40:41], v4, v3
	s_waitcnt vmcnt(0)
	s_cmp_lg_u32 s83, 0
	s_cbranch_scc0 .Lck_skip_l1
	ds_write_b128 v87, v[90:93]
	v_cvt_pk_bf16_f32 v87, v90, 0
	v_lshlrev_b32_e32 v87, 16, v87
	v_sub_f32_e32 v88, v90, v87
	v_cvt_pk_bf16_f32 v90, v88, 0
	v_lshlrev_b32_e32 v90, 16, v90
	v_cvt_pk_bf16_f32 v94, v87, v90
	v_cvt_pk_bf16_f32 v87, v91, 0
	v_sub_f32_e32 v88, v88, v90
	v_lshlrev_b32_e32 v87, 16, v87
	v_cvt_pk_bf16_f32 v95, v88, -1.0
	v_sub_f32_e32 v88, v91, v87
	v_cvt_pk_bf16_f32 v90, v88, 0
	v_lshlrev_b32_e32 v90, 16, v90
	v_cvt_pk_bf16_f32 v96, v87, v90
	v_cvt_pk_bf16_f32 v87, v92, 0
	v_sub_f32_e32 v88, v88, v90
	v_lshlrev_b32_e32 v87, 16, v87
	v_cvt_pk_bf16_f32 v97, v88, -1.0
	v_sub_f32_e32 v88, v92, v87
	v_cvt_pk_bf16_f32 v90, v88, 0
	v_lshlrev_b32_e32 v90, 16, v90
	v_sub_f32_e32 v88, v88, v90
	v_cvt_pk_bf16_f32 v90, v87, v90
	v_cvt_pk_bf16_f32 v87, v93, 0
	v_lshlrev_b32_e32 v87, 16, v87
	v_cvt_pk_bf16_f32 v91, v88, -1.0
	v_sub_f32_e32 v88, v93, v87
	v_cvt_pk_bf16_f32 v92, v88, 0
	v_lshlrev_b32_e32 v92, 16, v92
	v_sub_f32_e32 v88, v88, v92
	v_cvt_pk_bf16_f32 v92, v87, v92
	v_cvt_pk_bf16_f32 v93, v88, -1.0
	ds_write_b128 v86, v[94:97]
	ds_write_b128 v86, v[90:93] offset:16
.Lck_skip_l1:
	v_lshlrev_b32_e32 v54, 16, v22
	v_and_b32_e32 v55, 0xffff0000, v22
	v_lshlrev_b32_e32 v56, 16, v23
	v_and_b32_e32 v57, 0xffff0000, v23
	v_lshlrev_b32_e32 v22, 16, v24
	v_and_b32_e32 v23, 0xffff0000, v24
	v_lshlrev_b32_e32 v24, 16, v25
	v_and_b32_e32 v25, 0xffff0000, v25
	global_store_dwordx4 v[58:59], v[22:25], off offset:128
	v_or_b32_e32 v4, 16, v2
	v_cmp_gt_u32_e64 s[42:43], v4, v3
	v_lshlrev_b32_e32 v22, 16, v26
	v_and_b32_e32 v23, 0xffff0000, v26
	v_lshlrev_b32_e32 v24, 16, v27
	v_and_b32_e32 v25, 0xffff0000, v27
	global_store_dwordx4 v[60:61], v[22:25], off
	v_lshl_add_u64 v[26:27], v[58:59], 0, s[2:3]
	v_or_b32_e32 v4, 48, v2
	v_lshlrev_b32_e32 v22, 16, v28
	v_and_b32_e32 v23, 0xffff0000, v28
	v_lshlrev_b32_e32 v24, 16, v29
	v_and_b32_e32 v25, 0xffff0000, v29
	v_lshl_add_u64 v[28:29], v[60:61], 0, s[2:3]
	s_movk_i32 s2, 0x4000
	global_store_dwordx4 v[60:61], v[22:25], off offset:128
	v_cmp_gt_u32_e64 s[44:45], v4, v3
	v_or_b32_e32 v4, 17, v2
	v_lshlrev_b32_e32 v22, 16, v30
	v_and_b32_e32 v23, 0xffff0000, v30
	v_add_co_u32_e32 v30, vcc, s2, v58
	v_lshlrev_b32_e32 v24, 16, v31
	v_and_b32_e32 v25, 0xffff0000, v31
	v_addc_co_u32_e32 v31, vcc, 0, v59, vcc
	global_store_dwordx4 v[30:31], v[22:25], off
	v_cmp_gt_u32_e64 s[46:47], v4, v3
	v_or_b32_e32 v4, 49, v2
	v_lshlrev_b32_e32 v22, 16, v32
	v_and_b32_e32 v23, 0xffff0000, v32
	v_lshlrev_b32_e32 v24, 16, v33
	v_and_b32_e32 v25, 0xffff0000, v33
	global_store_dwordx4 v[26:27], v[22:25], off offset:128
	v_add_co_u32_e32 v26, vcc, s2, v60
	s_nop 0
	v_lshlrev_b32_e32 v22, 16, v34
	v_and_b32_e32 v23, 0xffff0000, v34
	v_lshlrev_b32_e32 v24, 16, v35
	v_and_b32_e32 v25, 0xffff0000, v35
	v_addc_co_u32_e32 v27, vcc, 0, v61, vcc
	global_store_dwordx4 v[26:27], v[22:25], off
	s_mov_b64 s[2:3], 0x8000
	v_lshl_add_u64 v[26:27], v[58:59], 0, s[2:3]
	v_lshlrev_b32_e32 v22, 16, v36
	v_and_b32_e32 v23, 0xffff0000, v36
	v_lshlrev_b32_e32 v24, 16, v37
	v_and_b32_e32 v25, 0xffff0000, v37
; #define LAS __attribute__((address_space(3)))
; __device__ __forceinline__ float bflo(unsigned w) { return __uint_as_float(w << 16); }
; __device__ __forceinline__ float bfhi(unsigned w) { return __uint_as_float(w & 0xffff0000u); }
; #define ATT_WAIT_BAR() asm volatile("s_waitcnt vmcnt(0) lgkmcnt(0)\n\ts_barrier" ::: "memory")
; template <int TYPE>
; __device__ __forceinline__ void conv_store(const ConvRegs& c, const Args& a, int l, int h, size_t rowq, int lane) {
; #pragma unroll
;     for (int i = 0; i < 4; ++i) { const size_t grow = rowq + i * 8 + (lane >> 3);
;         float* ko = a.out + (TYPE == 0 ? O_FKP : O_SKP) + ((size_t)l * MP + grow) * W + h * HD + (lane & 7) * 8;
;         float* vo = a.out + (TYPE == 0 ? O_FVP : O_SVP) + ((size_t)l * MP + grow) * W + h * HD + (lane & 7) * 8;
;         const u32x4 kw = c.k[i], vw = c.v[i];
;         __builtin_nontemporal_store((f32x4){bflo(kw.x), bfhi(kw.x), bflo(kw.y), bfhi(kw.y)}, (f32x4*)ko); __builtin_nontemporal_store((f32x4){bflo(kw.z), bfhi(kw.z), bflo(kw.w), bfhi(kw.w)}, (f32x4*)(ko + 4));
;         __builtin_nontemporal_store((f32x4){bflo(vw.x), bfhi(vw.x), bflo(vw.y), bfhi(vw.y)}, (f32x4*)vo); __builtin_nontemporal_store((f32x4){bflo(vw.z), bfhi(vw.z), bflo(vw.w), bfhi(vw.w)}, (f32x4*)(vo + 4)); }
; }
; __device__ __forceinline__ void prompt_unit_fox(const Args& a, int l, int b, int h, int qb, LAS unsigned char* lds) {
;     ...
;     const lds_cptr vp0 = (lds_cptr)lds + F_V + ((lane >> 4) & 1) * 32 + (lane & 3) * 8 + (4 * hi + ((lane & 15) >> 2)) * 64;
;     const int ql = 32 * (wid & 1) + r32, qlim = ql + 1;
;     LAS float* wsf = (LAS float*)(lds + F_WSF) + wid * 64;
;     FoxState st; st.m = 0.f; st.l = 0.f; st.mq = (bf16x8){}; st.o[0] = (f32x16){}; st.o[1] = (f32x16){};
;     PairP pp; bool pending = false;
; #pragma unroll
;     for (int i = 0; i < 8; ++i) pp.w[i] = (u32x4){0u, 0u, 0u, 0u};
;     { ConvRegs cv; conv_load(cv, a, rowb + q0 + wid * 32, col, lane); conv_store<0>(cv, a, l, h, rowb + q0 + wid * 32, lane); }
;     int slot = 0, pslot = 0;
;     ...
;         ATT_WAIT_BAR();
	global_store_dwordx4 v[28:29], v[22:25], off offset:128
	v_lshl_add_u64 v[28:29], v[60:61], 0, s[2:3]
	s_mov_b32 s2, 0x8000
	v_add_co_u32_e32 v30, vcc, s2, v58
	v_lshlrev_b32_e32 v22, 16, v38
	v_and_b32_e32 v23, 0xffff0000, v38
	v_lshlrev_b32_e32 v24, 16, v39
	v_and_b32_e32 v25, 0xffff0000, v39
	v_addc_co_u32_e32 v31, vcc, 0, v59, vcc
	global_store_dwordx4 v[30:31], v[22:25], off
	v_cmp_gt_u32_e64 s[48:49], v4, v3
	v_or_b32_e32 v4, 18, v2
	v_lshlrev_b32_e32 v22, 16, v40
	v_and_b32_e32 v23, 0xffff0000, v40
	v_lshlrev_b32_e32 v24, 16, v41
	v_and_b32_e32 v25, 0xffff0000, v41
	global_store_dwordx4 v[26:27], v[22:25], off offset:128
	v_add_co_u32_e32 v26, vcc, s2, v60
	v_cmp_gt_u32_e64 s[50:51], v4, v3
	v_or_b32_e32 v4, 50, v2
	v_lshlrev_b32_e32 v22, 16, v42
	v_and_b32_e32 v23, 0xffff0000, v42
	v_lshlrev_b32_e32 v24, 16, v43
	v_and_b32_e32 v25, 0xffff0000, v43
	v_addc_co_u32_e32 v27, vcc, 0, v61, vcc
	v_cmp_gt_u32_e64 s[52:53], v4, v3
	v_or_b32_e32 v4, 19, v2
	global_store_dwordx4 v[26:27], v[22:25], off
	s_mov_b64 s[2:3], 0xc000
	v_cmp_gt_u32_e64 s[54:55], v4, v3
	v_lshlrev_b32_e32 v22, 16, v44
	v_and_b32_e32 v23, 0xffff0000, v44
	v_lshlrev_b32_e32 v24, 16, v45
	v_and_b32_e32 v25, 0xffff0000, v45
	v_or_b32_e32 v4, 51, v2
	global_store_dwordx4 v[28:29], v[22:25], off offset:128
	v_lshl_add_u64 v[26:27], v[58:59], 0, s[2:3]
	v_lshl_add_u64 v[28:29], v[60:61], 0, s[2:3]
	s_mov_b32 s2, 0xc000
	v_cmp_gt_u32_e64 s[56:57], v4, v3
	v_or_b32_e32 v4, 24, v2
	v_add_co_u32_e32 v30, vcc, s2, v58
	v_cmp_gt_u32_e64 s[58:59], v4, v3
	v_or_b32_e32 v4, 56, v2
	v_lshlrev_b32_e32 v22, 16, v46
	v_and_b32_e32 v23, 0xffff0000, v46
	v_lshlrev_b32_e32 v24, 16, v47
	v_and_b32_e32 v25, 0xffff0000, v47
	v_addc_co_u32_e32 v31, vcc, 0, v59, vcc
	v_cmp_gt_u32_e64 s[60:61], v4, v3
	v_or_b32_e32 v4, 25, v2
	global_store_dwordx4 v[30:31], v[22:25], off
	v_cmp_gt_u32_e64 s[62:63], v4, v3
	v_or_b32_e32 v4, 57, v2
	v_lshlrev_b32_e32 v22, 16, v48
	v_and_b32_e32 v23, 0xffff0000, v48
	v_lshlrev_b32_e32 v24, 16, v49
	v_and_b32_e32 v25, 0xffff0000, v49
	global_store_dwordx4 v[26:27], v[22:25], off offset:128
	v_add_co_u32_e32 v26, vcc, s2, v60
	s_add_i32 s2, 0, 0x18000
	v_cmp_gt_u32_e64 s[64:65], v4, v3
	v_or_b32_e32 v4, 26, v2
	v_lshlrev_b32_e32 v22, 16, v50
	v_and_b32_e32 v23, 0xffff0000, v50
	v_lshlrev_b32_e32 v24, 16, v51
	v_and_b32_e32 v25, 0xffff0000, v51
	v_addc_co_u32_e32 v27, vcc, 0, v61, vcc
	v_add_u32_e32 v186, s2, v174
	s_add_i32 s2, 0, 0x1a800
	v_cmp_gt_u32_e64 s[66:67], v4, v3
	v_or_b32_e32 v4, 58, v2
	v_mov_b32_e32 v66, v5
	v_mov_b32_e32 v67, v5
	global_store_dwordx4 v[58:59], v[54:57], off
	global_store_dwordx4 v[26:27], v[22:25], off
	s_bitcmp1_b32 s6, 7
	v_cmp_gt_u32_e64 s[6:7], 32, v20
	v_lshlrev_b32_e32 v22, 16, v52
	v_and_b32_e32 v23, 0xffff0000, v52
	v_lshlrev_b32_e32 v24, 16, v53
	v_and_b32_e32 v25, 0xffff0000, v53
	v_cmp_gt_u32_e64 s[8:9], v2, v3
	v_cmp_lt_u32_e64 s[12:13], v2, v3
	v_cmp_gt_u32_e64 s[68:69], v4, v3
	v_or_b32_e32 v4, 27, v2
	v_or_b32_e32 v2, 59, v2
	v_mov_b32_e32 v52, v5
	v_mov_b32_e32 v53, v5
	v_mov_b32_e32 v54, v5
	v_mov_b32_e32 v55, v5
	v_mov_b32_e32 v56, v5
	v_mov_b32_e32 v57, v5
	v_mov_b32_e32 v58, v5
	v_mov_b32_e32 v59, v5
	v_mov_b32_e32 v60, v5
	v_mov_b32_e32 v61, v5
	v_mov_b32_e32 v62, v5
	v_mov_b32_e32 v63, v5
	v_mov_b32_e32 v64, v5
	v_mov_b32_e32 v65, v5
	v_mov_b64_e32 v[82:83], v[66:67]
	s_mov_b32 s75, 0
	v_lshl_add_u32 v188, v180, 3, s2
	s_cselect_b64 s[94:95], -1, 0
	v_lshlrev_b32_e32 v182, 10, v21
	v_lshlrev_b32_e32 v189, 4, v180
	v_cndmask_b32_e64 v122, 0, v183, s[6:7]
	v_cndmask_b32_e64 v121, 0, -1.0, s[6:7]
	v_mov_b32_e32 v120, v5
	v_mov_b32_e32 v123, v5
	v_cmp_gt_u32_e64 s[70:71], v4, v3
	v_cmp_gt_u32_e64 s[72:73], v2, v3
	v_lshl_add_u32 v184, v180, 2, s89
	v_mov_b32_e32 v156, v5
	v_mov_b32_e32 v157, v5
	v_mov_b32_e32 v158, v5
	v_mov_b32_e32 v159, v5
	v_mov_b32_e32 v192, 0
	s_mov_b64 s[2:3], 0
	v_mov_b32_e32 v124, 0
	v_mov_b32_e32 v125, 0
	v_mov_b32_e32 v126, 0
	v_mov_b32_e32 v127, 0
	v_mov_b32_e32 v128, 0
	v_mov_b32_e32 v129, 0
	v_mov_b32_e32 v130, 0
	v_mov_b32_e32 v131, 0
	v_mov_b32_e32 v132, 0
	v_mov_b32_e32 v133, 0
	v_mov_b32_e32 v134, 0
	v_mov_b32_e32 v135, 0
	v_mov_b32_e32 v136, 0
	v_mov_b32_e32 v137, 0
	v_mov_b32_e32 v138, 0
	v_mov_b32_e32 v139, 0
	v_mov_b32_e32 v140, 0
	v_mov_b32_e32 v141, 0
	v_mov_b32_e32 v142, 0
	v_mov_b32_e32 v143, 0
	v_mov_b32_e32 v144, 0
	v_mov_b32_e32 v145, 0
	v_mov_b32_e32 v146, 0
	v_mov_b32_e32 v147, 0
	v_mov_b32_e32 v148, 0
	v_mov_b32_e32 v149, 0
	v_mov_b32_e32 v150, 0
	v_mov_b32_e32 v151, 0
	v_mov_b32_e32 v152, 0
	v_mov_b32_e32 v153, 0
	v_mov_b32_e32 v154, 0
	v_mov_b32_e32 v155, 0
	v_cndmask_b32_e64 v2, 0, v185, s[6:7]
	s_mov_b32 s93, 0
	v_mov_b64_e32 v[80:81], v[64:65]
	v_mov_b64_e32 v[78:79], v[62:63]
	v_mov_b64_e32 v[76:77], v[60:61]
	v_mov_b64_e32 v[74:75], v[58:59]
	v_mov_b64_e32 v[72:73], v[56:57]
	v_mov_b64_e32 v[70:71], v[54:55]
	v_mov_b64_e32 v[68:69], v[52:53]
	v_mov_b32_e32 v193, 0
	global_store_dwordx4 v[28:29], v[22:25], off offset:128
	s_waitcnt vmcnt(16) lgkmcnt(0)
	s_barrier
	v_mov_b64_e32 v[20:21], 0
	v_mov_b64_e32 v[22:23], 0
	v_mov_b64_e32 v[24:25], 0
	v_mov_b64_e32 v[26:27], 0
	v_mov_b64_e32 v[28:29], 0
	v_mov_b64_e32 v[30:31], 0
	v_mov_b64_e32 v[32:33], 0
	v_mov_b64_e32 v[34:35], 0
	v_mov_b64_e32 v[36:37], 0
	v_mov_b64_e32 v[38:39], 0
	v_mov_b64_e32 v[40:41], 0
	v_mov_b64_e32 v[42:43], 0
	v_mov_b64_e32 v[44:45], 0
	v_mov_b64_e32 v[46:47], 0
	v_mov_b64_e32 v[48:49], 0
	v_mov_b64_e32 v[50:51], 0
	s_branch .Lfox_top_l1
